# rank-96 LoRA GEMMs (decay, iclr) run one K-loop trip (zero-padded K-tiles skipped), on top of w-from-global scan and conversion move
# speedup vs baseline: 1.0079x; 1.0040x over previous
.LBB0_596:
	s_ashr_i32 s25, s24, 31
	s_lshl_b64 s[26:27], s[24:25], 17
	s_add_u32 s26, s85, s26
	s_addc_u32 s27, s79, s27
	s_and_b64 s[28:29], s[0:1], exec
	s_cselect_b32 s25, s27, s43
	s_cselect_b32 s36, s26, s42
	s_ashr_i32 s23, s22, 31
	s_lshl_b64 s[28:29], s[22:23], 17
	s_add_u32 s28, s20, s28
	s_addc_u32 s29, s21, s29
	s_and_b64 s[44:45], s[0:1], exec
	v_mov_b32_e32 v2, 0
	s_cselect_b32 s23, s29, s41
	s_cselect_b32 s37, s28, s40
	s_mov_b64 s[68:69], 0
	s_mov_b64 s[52:53], 0
	s_mov_b64 s[54:55], -1
	v_mov_b32_e32 v3, v2
	v_mov_b32_e32 v4, v2
	v_mov_b32_e32 v5, v2
	v_mov_b32_e32 v34, v2
	v_mov_b32_e32 v35, v2
	v_mov_b32_e32 v36, v2
	v_mov_b32_e32 v37, v2
	v_mov_b32_e32 v6, v2
	v_mov_b32_e32 v7, v2
	v_mov_b32_e32 v8, v2
	v_mov_b32_e32 v9, v2
	v_mov_b32_e32 v38, v2
	v_mov_b32_e32 v39, v2
	v_mov_b32_e32 v40, v2
	v_mov_b32_e32 v41, v2
	v_mov_b32_e32 v10, v2
	v_mov_b32_e32 v11, v2
	v_mov_b32_e32 v12, v2
	v_mov_b32_e32 v13, v2
	v_mov_b32_e32 v42, v2
	v_mov_b32_e32 v43, v2
	v_mov_b32_e32 v44, v2
	v_mov_b32_e32 v45, v2
	v_mov_b32_e32 v14, v2
	v_mov_b32_e32 v15, v2
	v_mov_b32_e32 v16, v2
	v_mov_b32_e32 v17, v2
	v_mov_b32_e32 v46, v2
	v_mov_b32_e32 v47, v2
	v_mov_b32_e32 v48, v2
	v_mov_b32_e32 v49, v2
	v_mov_b32_e32 v66, v2
	v_mov_b32_e32 v67, v2
	v_mov_b32_e32 v68, v2
	v_mov_b32_e32 v69, v2
	v_mov_b32_e32 v98, v2
	v_mov_b32_e32 v99, v2
	v_mov_b32_e32 v100, v2
	v_mov_b32_e32 v101, v2
	v_mov_b32_e32 v70, v2
	v_mov_b32_e32 v71, v2
	v_mov_b32_e32 v72, v2
	v_mov_b32_e32 v73, v2
	v_mov_b32_e32 v102, v2
	v_mov_b32_e32 v103, v2
	v_mov_b32_e32 v104, v2
	v_mov_b32_e32 v105, v2
	v_mov_b32_e32 v74, v2
	v_mov_b32_e32 v75, v2
	v_mov_b32_e32 v76, v2
	v_mov_b32_e32 v77, v2
	v_mov_b32_e32 v106, v2
	v_mov_b32_e32 v107, v2
	v_mov_b32_e32 v108, v2
	v_mov_b32_e32 v109, v2
	v_mov_b32_e32 v78, v2
	v_mov_b32_e32 v79, v2
	v_mov_b32_e32 v80, v2
	v_mov_b32_e32 v81, v2
	v_mov_b32_e32 v110, v2
	v_mov_b32_e32 v111, v2
	v_mov_b32_e32 v112, v2
	v_mov_b32_e32 v113, v2
	v_mov_b32_e32 v18, v2
	v_mov_b32_e32 v19, v2
	v_mov_b32_e32 v20, v2
	v_mov_b32_e32 v21, v2
	v_mov_b32_e32 v50, v2
	v_mov_b32_e32 v51, v2
	v_mov_b32_e32 v52, v2
	v_mov_b32_e32 v53, v2
	v_mov_b32_e32 v22, v2
	v_mov_b32_e32 v23, v2
	v_mov_b32_e32 v24, v2
	v_mov_b32_e32 v25, v2
	v_mov_b32_e32 v54, v2
	v_mov_b32_e32 v55, v2
	v_mov_b32_e32 v56, v2
	v_mov_b32_e32 v57, v2
	v_mov_b32_e32 v26, v2
	v_mov_b32_e32 v27, v2
	v_mov_b32_e32 v28, v2
	v_mov_b32_e32 v29, v2
	v_mov_b32_e32 v58, v2
	v_mov_b32_e32 v59, v2
	v_mov_b32_e32 v60, v2
	v_mov_b32_e32 v61, v2
	v_mov_b32_e32 v30, v2
	v_mov_b32_e32 v31, v2
	v_mov_b32_e32 v32, v2
	v_mov_b32_e32 v33, v2
	v_mov_b32_e32 v62, v2
	v_mov_b32_e32 v63, v2
	v_mov_b32_e32 v64, v2
	v_mov_b32_e32 v65, v2
	v_mov_b32_e32 v82, v2
	v_mov_b32_e32 v83, v2
	v_mov_b32_e32 v84, v2
	v_mov_b32_e32 v85, v2
	v_mov_b32_e32 v114, v2
	v_mov_b32_e32 v115, v2
	v_mov_b32_e32 v116, v2
	v_mov_b32_e32 v117, v2
	v_mov_b32_e32 v86, v2
	v_mov_b32_e32 v87, v2
	v_mov_b32_e32 v88, v2
	v_mov_b32_e32 v89, v2
	v_mov_b32_e32 v122, v2
	v_mov_b32_e32 v123, v2
	v_mov_b32_e32 v124, v2
	v_mov_b32_e32 v125, v2
	v_mov_b32_e32 v90, v2
	v_mov_b32_e32 v91, v2
	v_mov_b32_e32 v92, v2
	v_mov_b32_e32 v93, v2
	v_mov_b32_e32 v126, v2
	v_mov_b32_e32 v127, v2
	v_mov_b32_e32 v128, v2
	v_mov_b32_e32 v129, v2
	v_mov_b32_e32 v94, v2
	v_mov_b32_e32 v95, v2
	v_mov_b32_e32 v96, v2
	v_mov_b32_e32 v97, v2
	v_mov_b32_e32 v130, v2
	v_mov_b32_e32 v131, v2
	v_mov_b32_e32 v132, v2
	v_mov_b32_e32 v133, v2

.LBB0_620:
	s_ashr_i32 s21, s20, 31
	s_lshl_b64 s[22:23], s[20:21], 17
	s_add_u32 s22, s62, s22
	s_addc_u32 s23, s63, s23
	s_and_b64 s[24:25], s[0:1], exec
	s_cselect_b32 s21, s23, s31
	s_cselect_b32 s36, s22, s30
	s_ashr_i32 s13, s12, 31
	s_lshl_b64 s[24:25], s[12:13], 17
	s_add_u32 s24, s18, s24
	s_addc_u32 s25, s19, s25
	s_and_b64 s[40:41], s[0:1], exec
	v_mov_b32_e32 v2, 0
	s_cselect_b32 s13, s25, s29
	s_cselect_b32 s37, s24, s28
	s_mov_b64 s[52:53], 0
	s_mov_b64 s[40:41], 0
	s_mov_b64 s[42:43], -1
	v_mov_b32_e32 v3, v2
	v_mov_b32_e32 v4, v2
	v_mov_b32_e32 v5, v2
	v_mov_b32_e32 v34, v2
	v_mov_b32_e32 v35, v2
	v_mov_b32_e32 v36, v2
	v_mov_b32_e32 v37, v2
	v_mov_b32_e32 v6, v2
	v_mov_b32_e32 v7, v2
	v_mov_b32_e32 v8, v2
	v_mov_b32_e32 v9, v2
	v_mov_b32_e32 v38, v2
	v_mov_b32_e32 v39, v2
	v_mov_b32_e32 v40, v2
	v_mov_b32_e32 v41, v2
	v_mov_b32_e32 v10, v2
	v_mov_b32_e32 v11, v2
	v_mov_b32_e32 v12, v2
	v_mov_b32_e32 v13, v2
	v_mov_b32_e32 v42, v2
	v_mov_b32_e32 v43, v2
	v_mov_b32_e32 v44, v2
	v_mov_b32_e32 v45, v2
	v_mov_b32_e32 v14, v2
	v_mov_b32_e32 v15, v2
	v_mov_b32_e32 v16, v2
	v_mov_b32_e32 v17, v2
	v_mov_b32_e32 v46, v2
	v_mov_b32_e32 v47, v2
	v_mov_b32_e32 v48, v2
	v_mov_b32_e32 v49, v2
	v_mov_b32_e32 v66, v2
	v_mov_b32_e32 v67, v2
	v_mov_b32_e32 v68, v2
	v_mov_b32_e32 v69, v2
	v_mov_b32_e32 v98, v2
	v_mov_b32_e32 v99, v2
	v_mov_b32_e32 v100, v2
	v_mov_b32_e32 v101, v2
	v_mov_b32_e32 v70, v2
	v_mov_b32_e32 v71, v2
	v_mov_b32_e32 v72, v2
	v_mov_b32_e32 v73, v2
	v_mov_b32_e32 v102, v2
	v_mov_b32_e32 v103, v2
	v_mov_b32_e32 v104, v2
	v_mov_b32_e32 v105, v2
	v_mov_b32_e32 v74, v2
	v_mov_b32_e32 v75, v2
	v_mov_b32_e32 v76, v2
	v_mov_b32_e32 v77, v2
	v_mov_b32_e32 v106, v2
	v_mov_b32_e32 v107, v2
	v_mov_b32_e32 v108, v2
	v_mov_b32_e32 v109, v2
	v_mov_b32_e32 v78, v2
	v_mov_b32_e32 v79, v2
	v_mov_b32_e32 v80, v2
	v_mov_b32_e32 v81, v2
	v_mov_b32_e32 v110, v2
	v_mov_b32_e32 v111, v2
	v_mov_b32_e32 v112, v2
	v_mov_b32_e32 v113, v2
	v_mov_b32_e32 v18, v2
	v_mov_b32_e32 v19, v2
	v_mov_b32_e32 v20, v2
	v_mov_b32_e32 v21, v2
	v_mov_b32_e32 v50, v2
	v_mov_b32_e32 v51, v2
	v_mov_b32_e32 v52, v2
	v_mov_b32_e32 v53, v2
	v_mov_b32_e32 v22, v2
	v_mov_b32_e32 v23, v2
	v_mov_b32_e32 v24, v2
	v_mov_b32_e32 v25, v2
	v_mov_b32_e32 v54, v2
	v_mov_b32_e32 v55, v2
	v_mov_b32_e32 v56, v2
	v_mov_b32_e32 v57, v2
	v_mov_b32_e32 v26, v2
	v_mov_b32_e32 v27, v2
	v_mov_b32_e32 v28, v2
	v_mov_b32_e32 v29, v2
	v_mov_b32_e32 v58, v2
	v_mov_b32_e32 v59, v2
	v_mov_b32_e32 v60, v2
	v_mov_b32_e32 v61, v2
	v_mov_b32_e32 v30, v2
	v_mov_b32_e32 v31, v2
	v_mov_b32_e32 v32, v2
	v_mov_b32_e32 v33, v2
	v_mov_b32_e32 v62, v2
	v_mov_b32_e32 v63, v2
	v_mov_b32_e32 v64, v2
	v_mov_b32_e32 v65, v2
	v_mov_b32_e32 v82, v2
	v_mov_b32_e32 v83, v2
	v_mov_b32_e32 v84, v2
	v_mov_b32_e32 v85, v2
	v_mov_b32_e32 v114, v2
	v_mov_b32_e32 v115, v2
	v_mov_b32_e32 v116, v2
	v_mov_b32_e32 v117, v2
	v_mov_b32_e32 v86, v2
	v_mov_b32_e32 v87, v2
	v_mov_b32_e32 v88, v2
	v_mov_b32_e32 v89, v2
	v_mov_b32_e32 v118, v2
	v_mov_b32_e32 v119, v2
	v_mov_b32_e32 v120, v2
	v_mov_b32_e32 v121, v2
	v_mov_b32_e32 v90, v2
	v_mov_b32_e32 v91, v2
	v_mov_b32_e32 v92, v2
	v_mov_b32_e32 v93, v2
	v_mov_b32_e32 v126, v2
	v_mov_b32_e32 v127, v2
	v_mov_b32_e32 v128, v2
	v_mov_b32_e32 v129, v2
	v_mov_b32_e32 v94, v2
	v_mov_b32_e32 v95, v2
	v_mov_b32_e32 v96, v2
	v_mov_b32_e32 v97, v2
	v_mov_b32_e32 v130, v2
	v_mov_b32_e32 v131, v2
	v_mov_b32_e32 v132, v2
	v_mov_b32_e32 v133, v2
